# all five GEMMs peeled + SwiGLU epilogue's first LDS operand reads hoisted above the alignment barrier
# speedup vs baseline: 1.0131x; 1.0043x over previous
; #define PG8_LAS __attribute__((address_space(3)))
; __device__ __forceinline__ unsigned cvt_pk_bf16(float lo, float hi) { unsigned r; asm volatile("v_cvt_pk_bf16_f32 %0, %1, %2" : "=v"(r) : "v"(lo), "v"(hi)); return r; }
; #define PG8_BAR __builtin_amdgcn_s_barrier()
;     __device__ __forceinline__ void operator()(const f32x4 (&acc)[2][2][4][2], const Unit& u, int wr, int wc, int fr, int fq, PG8_LAS unsigned char* sl) const {
;         const int row0 = u.pm * BM + wr * 64 + fr, col0 = u.pn * HALF + wc * 32 + 8 * fq;
;         const PG8_LAS float* sf = (const PG8_LAS float*)sl;
;         f32x4 bw[2][2];
; #pragma unroll
;         for (int bj = 0; bj < 2; ++bj)
; #pragma unroll
;             for (int n = 0; n < 2; ++n) bw[bj][n] = *(const PG8_LAS f32x4*)(sf + 128 + bj * 32 + 8 * fq + 4 * n);
; #pragma unroll
;         for (int ai = 0; ai < 2; ++ai)
; #pragma unroll
;             for (int m = 0; m < 4; ++m) { const int row = row0 + ai * HALF + m * 16; bf16_t* rowp = O + (size_t)row * ldc + col0;
;                 const float rs = __builtin_amdgcn_rsqf(sf[ai * 64 + m * 16 + fr] * (1.0f / 2048.0f) + 1e-6f);
;                 const f32x4 a0 = acc[ai][0][m][0] * rs + bw[0][0], a1 = acc[ai][0][m][1] * rs + bw[0][1], b0 = acc[ai][1][m][0] * rs + bw[1][0], b1 = acc[ai][1][m][1] * rs + bw[1][1];
;                 const f32x2 s0 = silu_mul_pk((f32x2){a0[0], a0[1]}, (f32x2){b0[0], b0[1]}), s1 = silu_mul_pk((f32x2){a0[2], a0[3]}, (f32x2){b0[2], b0[3]});
;                 const f32x2 s2 = silu_mul_pk((f32x2){a1[0], a1[1]}, (f32x2){b1[0], b1[1]}), s3 = silu_mul_pk((f32x2){a1[2], a1[3]}, (f32x2){b1[2], b1[3]});
;                 u32x4 w; w.x = cvt_pk_bf16(s0.x, s0.y); w.y = cvt_pk_bf16(s1.x, s1.y); w.z = cvt_pk_bf16(s2.x, s2.y); w.w = cvt_pk_bf16(s3.x, s3.y);
;                 *(u32x4*)rowp = w; }
; template <class Epi, class Sched, bool ALIGN_EPI = false, bool SP2 = false>
; __device__ __forceinline__ void gemm_phase(PG8_LAS unsigned char* lds, const Gemm g, const Sched& S, const Epi& E, const int tid) {
;     ...
;         if constexpr (ALIGN_EPI) { if (wr == 0) PG8_BAR; }
;         for (int er = 0; er < Epi::REP; ++er) { E(acc, cur, wr, wc, fr, fq, lds + EPI_LDS_OFF + wid * 1024); if (Epi::REP > 1) asm volatile("" ::: "memory"); }
.LBB0_269:
	ds_read_b32 v128, v163
	ds_read_b128 v[144:147], v162 offset:512
	s_and_b64 vcc, exec, s[12:13]
	s_cbranch_vccz .LBB0_271
	s_barrier
.LBB0_271:
	v_lshl_or_b32 v168, s74, 7, v164
	v_add_u32_e32 v166, s22, v160
	v_ashrrev_i32_e32 v169, 31, v168
	s_waitcnt lgkmcnt(0)
	v_fmamk_f32 v128, v128, 0x3a000000, v233
	v_rsq_f32_e32 v170, v128
	ds_read_b128 v[140:143], v162 offset:528
	ds_read_b128 v[132:135], v162 offset:640
	ds_read_b128 v[128:131], v162 offset:656
	s_andn2_b64 vcc, exec, s[6:7]
	s_mov_b64 s[6:7], -1
	v_pk_fma_f32 v[138:139], v[138:139], v[170:171], v[146:147] op_sel_hi:[1,0,1]
	v_pk_fma_f32 v[136:137], v[136:137], v[170:171], v[144:145] op_sel_hi:[1,0,1]
	s_waitcnt lgkmcnt(0)
	v_pk_fma_f32 v[126:127], v[126:127], v[170:171], v[142:143] op_sel_hi:[1,0,1]
	v_pk_fma_f32 v[122:123], v[122:123], v[170:171], v[134:135] op_sel_hi:[1,0,1]
	v_pk_fma_f32 v[124:125], v[124:125], v[170:171], v[140:141] op_sel_hi:[1,0,1]
	v_pk_fma_f32 v[120:121], v[120:121], v[170:171], v[132:133] op_sel_hi:[1,0,1]
	v_pk_fma_f32 v[116:117], v[116:117], v[170:171], v[128:129] op_sel_hi:[1,0,1]
	v_pk_fma_f32 v[118:119], v[118:119], v[170:171], v[130:131] op_sel_hi:[1,0,1]
	v_pk_mul_f32 v[170:171], v[136:137], s[72:73] op_sel_hi:[1,0]
	v_pk_mul_f32 v[172:173], v[138:139], s[72:73] op_sel_hi:[1,0]
	v_pk_mul_f32 v[122:123], v[138:139], v[122:123]
	v_pk_mul_f32 v[138:139], v[126:127], s[72:73] op_sel_hi:[1,0]
	v_exp_f32_e32 v170, v170
	v_exp_f32_e32 v171, v171
	v_exp_f32_e32 v172, v172
	v_exp_f32_e32 v173, v173
	v_pk_mul_f32 v[120:121], v[136:137], v[120:121]
	v_pk_mul_f32 v[136:137], v[124:125], s[72:73] op_sel_hi:[1,0]
	v_exp_f32_e32 v138, v138
	v_exp_f32_e32 v139, v139
	v_exp_f32_e32 v136, v136
	v_exp_f32_e32 v137, v137
	v_pk_add_f32 v[170:171], v[170:171], 1.0 op_sel_hi:[1,0]
	v_pk_add_f32 v[172:173], v[172:173], 1.0 op_sel_hi:[1,0]
	v_pk_add_f32 v[138:139], v[138:139], 1.0 op_sel_hi:[1,0]
	v_rcp_f32_e32 v170, v170
	v_rcp_f32_e32 v171, v171
	v_rcp_f32_e32 v172, v172
	v_rcp_f32_e32 v173, v173
	v_pk_add_f32 v[136:137], v[136:137], 1.0 op_sel_hi:[1,0]
	v_rcp_f32_e32 v138, v138
	v_rcp_f32_e32 v139, v139
	v_rcp_f32_e32 v136, v136
	v_rcp_f32_e32 v137, v137
	v_pk_mul_f32 v[118:119], v[126:127], v[118:119]
	v_pk_mul_f32 v[120:121], v[120:121], v[170:171]
	v_pk_mul_f32 v[122:123], v[122:123], v[172:173]
	v_pk_mul_f32 v[116:117], v[124:125], v[116:117]
	v_pk_mul_f32 v[118:119], v[118:119], v[138:139]
	v_pk_mul_f32 v[116:117], v[116:117], v[136:137]
	v_cvt_pk_bf16_f32 v120, v120, v121
	v_cvt_pk_bf16_f32 v121, v122, v123
	s_nop 0
	v_cvt_pk_bf16_f32 v122, v116, v117
	v_cvt_pk_bf16_f32 v123, v118, v119
	ds_read_b32 v118, v163 offset:64
	v_mov_b64_e32 v[116:117], s[92:93]
	v_mad_i64_i32 v[124:125], s[22:23], v166, s34, v[116:117]
	s_waitcnt lgkmcnt(0)
	v_fmamk_f32 v118, v118, 0x3a000000, v233
	v_rsq_f32_e32 v126, v118
	v_lshlrev_b64 v[118:119], 1, v[168:169]
	v_lshl_add_u64 v[124:125], v[124:125], 0, v[118:119]
	global_store_dwordx4 v[124:125], v[120:123], off
	v_pk_fma_f32 v[112:113], v[112:113], v[126:127], v[144:145] op_sel_hi:[1,0,1]
	v_pk_fma_f32 v[114:115], v[114:115], v[126:127], v[146:147] op_sel_hi:[1,0,1]
	v_pk_fma_f32 v[110:111], v[110:111], v[126:127], v[142:143] op_sel_hi:[1,0,1]
	v_pk_fma_f32 v[108:109], v[108:109], v[126:127], v[140:141] op_sel_hi:[1,0,1]
	v_pk_fma_f32 v[104:105], v[104:105], v[126:127], v[132:133] op_sel_hi:[1,0,1]
	v_pk_fma_f32 v[106:107], v[106:107], v[126:127], v[134:135] op_sel_hi:[1,0,1]
	v_pk_mul_f32 v[120:121], v[112:113], s[72:73] op_sel_hi:[1,0]
	v_pk_mul_f32 v[122:123], v[114:115], s[72:73] op_sel_hi:[1,0]
	v_exp_f32_e32 v120, v120
	v_exp_f32_e32 v121, v121
	v_pk_mul_f32 v[106:107], v[114:115], v[106:107]
	v_pk_mul_f32 v[104:105], v[112:113], v[104:105]
	v_pk_mul_f32 v[112:113], v[108:109], s[72:73] op_sel_hi:[1,0]
	v_pk_mul_f32 v[114:115], v[110:111], s[72:73] op_sel_hi:[1,0]
	v_exp_f32_e32 v122, v122
	v_exp_f32_e32 v123, v123
	v_exp_f32_e32 v112, v112
	v_exp_f32_e32 v113, v113
	v_exp_f32_e32 v114, v114
	v_exp_f32_e32 v115, v115
	v_pk_add_f32 v[120:121], v[120:121], 1.0 op_sel_hi:[1,0]
	v_pk_add_f32 v[122:123], v[122:123], 1.0 op_sel_hi:[1,0]
	v_rcp_f32_e32 v120, v120
	v_rcp_f32_e32 v121, v121
	v_pk_add_f32 v[112:113], v[112:113], 1.0 op_sel_hi:[1,0]
	v_pk_add_f32 v[114:115], v[114:115], 1.0 op_sel_hi:[1,0]
	v_rcp_f32_e32 v122, v122
	v_rcp_f32_e32 v123, v123
	v_rcp_f32_e32 v112, v112
	v_rcp_f32_e32 v113, v113
	v_rcp_f32_e32 v114, v114
	v_rcp_f32_e32 v115, v115
	v_pk_fma_f32 v[100:101], v[100:101], v[126:127], v[128:129] op_sel_hi:[1,0,1]
	v_pk_fma_f32 v[102:103], v[102:103], v[126:127], v[130:131] op_sel_hi:[1,0,1]
	v_pk_mul_f32 v[104:105], v[104:105], v[120:121]
	v_pk_mul_f32 v[102:103], v[110:111], v[102:103]
	v_pk_mul_f32 v[100:101], v[108:109], v[100:101]
	v_pk_mul_f32 v[106:107], v[106:107], v[122:123]
	v_pk_mul_f32 v[108:109], v[100:101], v[112:113]
	v_pk_mul_f32 v[110:111], v[102:103], v[114:115]
	v_cvt_pk_bf16_f32 v100, v104, v105
	v_cvt_pk_bf16_f32 v101, v106, v107
	v_cvt_pk_bf16_f32 v102, v108, v109
	v_or_b32_e32 v105, 16, v166
	v_cvt_pk_bf16_f32 v103, v110, v111
	ds_read_b32 v104, v163 offset:128
	v_mad_i64_i32 v[106:107], s[22:23], v105, s34, v[116:117]
	v_lshl_add_u64 v[106:107], v[106:107], 0, v[118:119]
	global_store_dwordx4 v[106:107], v[100:103], off
	s_waitcnt lgkmcnt(0)
; __device__ __forceinline__ unsigned cvt_pk_bf16(float lo, float hi) { unsigned r; asm volatile("v_cvt_pk_bf16_f32 %0, %1, %2" : "=v"(r) : "v"(lo), "v"(hi)); return r; }
;     __device__ __forceinline__ void operator()(const f32x4 (&acc)[2][2][4][2], const Unit& u, int wr, int wc, int fr, int fq, PG8_LAS unsigned char* sl) const {
;     ...
;             for (int m = 0; m < 4; ++m) { const int row = row0 + ai * HALF + m * 16; bf16_t* rowp = O + (size_t)row * ldc + col0;
;                 const float rs = __builtin_amdgcn_rsqf(sf[ai * 64 + m * 16 + fr] * (1.0f / 2048.0f) + 1e-6f);
;                 const f32x4 a0 = acc[ai][0][m][0] * rs + bw[0][0], a1 = acc[ai][0][m][1] * rs + bw[0][1], b0 = acc[ai][1][m][0] * rs + bw[1][0], b1 = acc[ai][1][m][1] * rs + bw[1][1];
;                 const f32x2 s0 = silu_mul_pk((f32x2){a0[0], a0[1]}, (f32x2){b0[0], b0[1]}), s1 = silu_mul_pk((f32x2){a0[2], a0[3]}, (f32x2){b0[2], b0[3]});
;                 const f32x2 s2 = silu_mul_pk((f32x2){a1[0], a1[1]}, (f32x2){b1[0], b1[1]}), s3 = silu_mul_pk((f32x2){a1[2], a1[3]}, (f32x2){b1[2], b1[3]});
;                 u32x4 w; w.x = cvt_pk_bf16(s0.x, s0.y); w.y = cvt_pk_bf16(s1.x, s1.y); w.z = cvt_pk_bf16(s2.x, s2.y); w.w = cvt_pk_bf16(s3.x, s3.y);
;                 *(u32x4*)rowp = w; }
	v_fmamk_f32 v104, v104, 0x3a000000, v233
	v_rsq_f32_e32 v104, v104
	s_nop 0
	v_pk_fma_f32 v[96:97], v[96:97], v[104:105], v[144:145] op_sel_hi:[1,0,1]
	v_pk_fma_f32 v[98:99], v[98:99], v[104:105], v[146:147] op_sel_hi:[1,0,1]
	v_pk_fma_f32 v[94:95], v[94:95], v[104:105], v[142:143] op_sel_hi:[1,0,1]
	v_pk_fma_f32 v[92:93], v[92:93], v[104:105], v[140:141] op_sel_hi:[1,0,1]
	v_pk_fma_f32 v[88:89], v[88:89], v[104:105], v[132:133] op_sel_hi:[1,0,1]
	v_pk_fma_f32 v[90:91], v[90:91], v[104:105], v[134:135] op_sel_hi:[1,0,1]
	v_pk_mul_f32 v[100:101], v[96:97], s[72:73] op_sel_hi:[1,0]
	v_pk_mul_f32 v[102:103], v[98:99], s[72:73] op_sel_hi:[1,0]
	v_exp_f32_e32 v100, v100
	v_exp_f32_e32 v101, v101
	v_pk_mul_f32 v[90:91], v[98:99], v[90:91]
	v_pk_mul_f32 v[88:89], v[96:97], v[88:89]
	v_pk_mul_f32 v[96:97], v[92:93], s[72:73] op_sel_hi:[1,0]
	v_pk_mul_f32 v[98:99], v[94:95], s[72:73] op_sel_hi:[1,0]
	v_exp_f32_e32 v102, v102
	v_exp_f32_e32 v103, v103
	v_exp_f32_e32 v96, v96
	v_exp_f32_e32 v97, v97
	v_exp_f32_e32 v98, v98
	v_exp_f32_e32 v99, v99
	v_pk_add_f32 v[100:101], v[100:101], 1.0 op_sel_hi:[1,0]
	v_pk_add_f32 v[102:103], v[102:103], 1.0 op_sel_hi:[1,0]
	v_rcp_f32_e32 v100, v100
	v_rcp_f32_e32 v101, v101
	v_pk_add_f32 v[96:97], v[96:97], 1.0 op_sel_hi:[1,0]
	v_pk_add_f32 v[98:99], v[98:99], 1.0 op_sel_hi:[1,0]
	v_rcp_f32_e32 v102, v102
	v_rcp_f32_e32 v103, v103
	v_rcp_f32_e32 v96, v96
	v_rcp_f32_e32 v97, v97
	v_rcp_f32_e32 v98, v98
	v_rcp_f32_e32 v99, v99
	v_pk_fma_f32 v[84:85], v[84:85], v[104:105], v[128:129] op_sel_hi:[1,0,1]
	v_pk_fma_f32 v[86:87], v[86:87], v[104:105], v[130:131] op_sel_hi:[1,0,1]
	v_pk_mul_f32 v[88:89], v[88:89], v[100:101]
	v_pk_mul_f32 v[86:87], v[94:95], v[86:87]
	v_pk_mul_f32 v[84:85], v[92:93], v[84:85]
	v_pk_mul_f32 v[90:91], v[90:91], v[102:103]
	v_pk_mul_f32 v[92:93], v[84:85], v[96:97]
	v_pk_mul_f32 v[94:95], v[86:87], v[98:99]
	v_cvt_pk_bf16_f32 v84, v88, v89
	v_cvt_pk_bf16_f32 v85, v90, v91
	v_cvt_pk_bf16_f32 v86, v92, v93
	v_or_b32_e32 v89, 32, v166
	v_cvt_pk_bf16_f32 v87, v94, v95
	ds_read_b32 v88, v163 offset:192
	v_mad_i64_i32 v[90:91], s[22:23], v89, s34, v[116:117]
	v_lshl_add_u64 v[90:91], v[90:91], 0, v[118:119]
	global_store_dwordx4 v[90:91], v[84:87], off
	s_waitcnt lgkmcnt(0)
	v_fmamk_f32 v88, v88, 0x3a000000, v233
	v_rsq_f32_e32 v88, v88
	s_nop 0
	v_pk_fma_f32 v[80:81], v[80:81], v[88:89], v[144:145] op_sel_hi:[1,0,1]
	v_pk_fma_f32 v[82:83], v[82:83], v[88:89], v[146:147] op_sel_hi:[1,0,1]
	v_pk_fma_f32 v[78:79], v[78:79], v[88:89], v[142:143] op_sel_hi:[1,0,1]
	v_pk_fma_f32 v[76:77], v[76:77], v[88:89], v[140:141] op_sel_hi:[1,0,1]
	v_pk_fma_f32 v[72:73], v[72:73], v[88:89], v[132:133] op_sel_hi:[1,0,1]
	v_pk_fma_f32 v[74:75], v[74:75], v[88:89], v[134:135] op_sel_hi:[1,0,1]
	v_pk_mul_f32 v[84:85], v[80:81], s[72:73] op_sel_hi:[1,0]
	v_pk_mul_f32 v[86:87], v[82:83], s[72:73] op_sel_hi:[1,0]
	v_exp_f32_e32 v84, v84
	v_exp_f32_e32 v85, v85
	v_pk_mul_f32 v[74:75], v[82:83], v[74:75]
	v_pk_mul_f32 v[72:73], v[80:81], v[72:73]
	v_pk_mul_f32 v[80:81], v[76:77], s[72:73] op_sel_hi:[1,0]
	v_pk_mul_f32 v[82:83], v[78:79], s[72:73] op_sel_hi:[1,0]
	v_exp_f32_e32 v86, v86
	v_exp_f32_e32 v87, v87
	v_exp_f32_e32 v80, v80
	v_exp_f32_e32 v81, v81
	v_exp_f32_e32 v82, v82
	v_exp_f32_e32 v83, v83
	v_pk_add_f32 v[84:85], v[84:85], 1.0 op_sel_hi:[1,0]
	v_pk_add_f32 v[86:87], v[86:87], 1.0 op_sel_hi:[1,0]
	v_rcp_f32_e32 v84, v84
	v_rcp_f32_e32 v85, v85
	v_pk_add_f32 v[80:81], v[80:81], 1.0 op_sel_hi:[1,0]
	v_pk_add_f32 v[82:83], v[82:83], 1.0 op_sel_hi:[1,0]
	v_rcp_f32_e32 v86, v86
	v_rcp_f32_e32 v87, v87
	v_rcp_f32_e32 v80, v80
	v_rcp_f32_e32 v81, v81
	v_rcp_f32_e32 v82, v82
	v_rcp_f32_e32 v83, v83
	v_pk_fma_f32 v[68:69], v[68:69], v[88:89], v[128:129] op_sel_hi:[1,0,1]
	v_pk_fma_f32 v[70:71], v[70:71], v[88:89], v[130:131] op_sel_hi:[1,0,1]
	v_pk_mul_f32 v[72:73], v[72:73], v[84:85]
	v_pk_mul_f32 v[70:71], v[78:79], v[70:71]
	v_pk_mul_f32 v[68:69], v[76:77], v[68:69]
	v_pk_mul_f32 v[74:75], v[74:75], v[86:87]
	v_pk_mul_f32 v[76:77], v[68:69], v[80:81]
	v_pk_mul_f32 v[78:79], v[70:71], v[82:83]
	v_cvt_pk_bf16_f32 v68, v72, v73
	v_cvt_pk_bf16_f32 v69, v74, v75
	v_cvt_pk_bf16_f32 v70, v76, v77
	v_or_b32_e32 v73, 48, v166
	v_cvt_pk_bf16_f32 v71, v78, v79
	ds_read_b32 v72, v163 offset:256
	v_mad_i64_i32 v[74:75], s[22:23], v73, s34, v[116:117]
	v_lshl_add_u64 v[74:75], v[74:75], 0, v[118:119]
	global_store_dwordx4 v[74:75], v[68:71], off
	s_waitcnt lgkmcnt(0)
	v_fmamk_f32 v72, v72, 0x3a000000, v233
	v_rsq_f32_e32 v72, v72
	s_nop 0
	v_pk_fma_f32 v[64:65], v[64:65], v[72:73], v[144:145] op_sel_hi:[1,0,1]
	v_pk_fma_f32 v[66:67], v[66:67], v[72:73], v[146:147] op_sel_hi:[1,0,1]
	v_pk_fma_f32 v[62:63], v[62:63], v[72:73], v[142:143] op_sel_hi:[1,0,1]
	v_pk_fma_f32 v[60:61], v[60:61], v[72:73], v[140:141] op_sel_hi:[1,0,1]
	v_pk_fma_f32 v[56:57], v[56:57], v[72:73], v[132:133] op_sel_hi:[1,0,1]
	v_pk_fma_f32 v[58:59], v[58:59], v[72:73], v[134:135] op_sel_hi:[1,0,1]
	v_pk_mul_f32 v[68:69], v[64:65], s[72:73] op_sel_hi:[1,0]
	v_pk_mul_f32 v[70:71], v[66:67], s[72:73] op_sel_hi:[1,0]
	v_exp_f32_e32 v68, v68
	v_exp_f32_e32 v69, v69
	v_pk_mul_f32 v[58:59], v[66:67], v[58:59]
	v_pk_mul_f32 v[56:57], v[64:65], v[56:57]
	v_pk_mul_f32 v[64:65], v[60:61], s[72:73] op_sel_hi:[1,0]
	v_pk_mul_f32 v[66:67], v[62:63], s[72:73] op_sel_hi:[1,0]
	v_exp_f32_e32 v70, v70
	v_exp_f32_e32 v71, v71
	v_exp_f32_e32 v64, v64
	v_exp_f32_e32 v65, v65
	v_exp_f32_e32 v66, v66
	v_exp_f32_e32 v67, v67
	v_pk_add_f32 v[68:69], v[68:69], 1.0 op_sel_hi:[1,0]
	v_pk_add_f32 v[70:71], v[70:71], 1.0 op_sel_hi:[1,0]
	v_rcp_f32_e32 v68, v68
	v_rcp_f32_e32 v69, v69
	v_pk_add_f32 v[64:65], v[64:65], 1.0 op_sel_hi:[1,0]
	v_pk_add_f32 v[66:67], v[66:67], 1.0 op_sel_hi:[1,0]
	v_rcp_f32_e32 v70, v70
	v_rcp_f32_e32 v71, v71
	v_rcp_f32_e32 v64, v64
	v_rcp_f32_e32 v65, v65
	v_rcp_f32_e32 v66, v66
	v_rcp_f32_e32 v67, v67
	v_pk_fma_f32 v[52:53], v[52:53], v[72:73], v[128:129] op_sel_hi:[1,0,1]
	v_pk_fma_f32 v[54:55], v[54:55], v[72:73], v[130:131] op_sel_hi:[1,0,1]
	v_pk_mul_f32 v[56:57], v[56:57], v[68:69]
	v_pk_mul_f32 v[54:55], v[62:63], v[54:55]
	v_pk_mul_f32 v[52:53], v[60:61], v[52:53]
	v_pk_mul_f32 v[58:59], v[58:59], v[70:71]
	v_pk_mul_f32 v[60:61], v[52:53], v[64:65]
	v_pk_mul_f32 v[62:63], v[54:55], v[66:67]
	v_cvt_pk_bf16_f32 v52, v56, v57
	v_cvt_pk_bf16_f32 v53, v58, v59
	v_cvt_pk_bf16_f32 v54, v60, v61
	v_add_u32_e32 v57, 0x80, v166
	v_cvt_pk_bf16_f32 v55, v62, v63
	ds_read_b32 v56, v163 offset:320
	v_mad_i64_i32 v[58:59], s[22:23], v57, s34, v[116:117]
	v_lshl_add_u64 v[58:59], v[58:59], 0, v[118:119]
	global_store_dwordx4 v[58:59], v[52:55], off
	s_waitcnt lgkmcnt(0)
; __device__ __forceinline__ unsigned cvt_pk_bf16(float lo, float hi) { unsigned r; asm volatile("v_cvt_pk_bf16_f32 %0, %1, %2" : "=v"(r) : "v"(lo), "v"(hi)); return r; }
; #define PG8_BAR __builtin_amdgcn_s_barrier()
;     __device__ __forceinline__ void operator()(const f32x4 (&acc)[2][2][4][2], const Unit& u, int wr, int wc, int fr, int fq, PG8_LAS unsigned char* sl) const {
;     ...
;             for (int m = 0; m < 4; ++m) { const int row = row0 + ai * HALF + m * 16; bf16_t* rowp = O + (size_t)row * ldc + col0;
;                 const float rs = __builtin_amdgcn_rsqf(sf[ai * 64 + m * 16 + fr] * (1.0f / 2048.0f) + 1e-6f);
;                 const f32x4 a0 = acc[ai][0][m][0] * rs + bw[0][0], a1 = acc[ai][0][m][1] * rs + bw[0][1], b0 = acc[ai][1][m][0] * rs + bw[1][0], b1 = acc[ai][1][m][1] * rs + bw[1][1];
;                 const f32x2 s0 = silu_mul_pk((f32x2){a0[0], a0[1]}, (f32x2){b0[0], b0[1]}), s1 = silu_mul_pk((f32x2){a0[2], a0[3]}, (f32x2){b0[2], b0[3]});
;                 const f32x2 s2 = silu_mul_pk((f32x2){a1[0], a1[1]}, (f32x2){b1[0], b1[1]}), s3 = silu_mul_pk((f32x2){a1[2], a1[3]}, (f32x2){b1[2], b1[3]});
;                 u32x4 w; w.x = cvt_pk_bf16(s0.x, s0.y); w.y = cvt_pk_bf16(s1.x, s1.y); w.z = cvt_pk_bf16(s2.x, s2.y); w.w = cvt_pk_bf16(s3.x, s3.y);
;                 *(u32x4*)rowp = w; }
; template <class Epi, class Sched, bool ALIGN_EPI = false, bool SP2 = false>
; __device__ __forceinline__ void gemm_phase(PG8_LAS unsigned char* lds, const Gemm g, const Sched& S, const Epi& E, const int tid) {
;     ...
;         if (!has_next) break;
; #pragma unroll
;         for (int a = 0; a < 2; ++a)
; #pragma unroll
;             for (int b = 0; b < 2; ++b)
; #pragma unroll
;                 for (int m = 0; m < 4; ++m)
; #pragma unroll
;                     for (int n = 0; n < 2; ++n) acc[a][b][m][n] = (f32x4){0.f, 0.f, 0.f, 0.f};
;         cur = nxt; cA = nA; cB = nB; ++ui;
;         if constexpr (ALIGN_EPI) { if (wr == 1) PG8_BAR; }
	v_fmamk_f32 v56, v56, 0x3a000000, v233
	v_rsq_f32_e32 v56, v56
	s_nop 0
	v_pk_fma_f32 v[48:49], v[48:49], v[56:57], v[144:145] op_sel_hi:[1,0,1]
	v_pk_fma_f32 v[50:51], v[50:51], v[56:57], v[146:147] op_sel_hi:[1,0,1]
	v_pk_fma_f32 v[46:47], v[46:47], v[56:57], v[142:143] op_sel_hi:[1,0,1]
	v_pk_fma_f32 v[44:45], v[44:45], v[56:57], v[140:141] op_sel_hi:[1,0,1]
	v_pk_fma_f32 v[40:41], v[40:41], v[56:57], v[132:133] op_sel_hi:[1,0,1]
	v_pk_fma_f32 v[42:43], v[42:43], v[56:57], v[134:135] op_sel_hi:[1,0,1]
	v_pk_mul_f32 v[52:53], v[48:49], s[72:73] op_sel_hi:[1,0]
	v_pk_mul_f32 v[54:55], v[50:51], s[72:73] op_sel_hi:[1,0]
	v_exp_f32_e32 v52, v52
	v_exp_f32_e32 v53, v53
	v_pk_mul_f32 v[42:43], v[50:51], v[42:43]
	v_pk_mul_f32 v[40:41], v[48:49], v[40:41]
	v_pk_mul_f32 v[48:49], v[44:45], s[72:73] op_sel_hi:[1,0]
	v_pk_mul_f32 v[50:51], v[46:47], s[72:73] op_sel_hi:[1,0]
	v_exp_f32_e32 v54, v54
	v_exp_f32_e32 v55, v55
	v_exp_f32_e32 v48, v48
	v_exp_f32_e32 v49, v49
	v_exp_f32_e32 v50, v50
	v_exp_f32_e32 v51, v51
	v_pk_add_f32 v[52:53], v[52:53], 1.0 op_sel_hi:[1,0]
	v_pk_add_f32 v[54:55], v[54:55], 1.0 op_sel_hi:[1,0]
	v_rcp_f32_e32 v52, v52
	v_rcp_f32_e32 v53, v53
	v_pk_add_f32 v[48:49], v[48:49], 1.0 op_sel_hi:[1,0]
	v_pk_add_f32 v[50:51], v[50:51], 1.0 op_sel_hi:[1,0]
	v_rcp_f32_e32 v54, v54
	v_rcp_f32_e32 v55, v55
	v_rcp_f32_e32 v48, v48
	v_rcp_f32_e32 v49, v49
	v_rcp_f32_e32 v50, v50
	v_rcp_f32_e32 v51, v51
	v_pk_fma_f32 v[36:37], v[36:37], v[56:57], v[128:129] op_sel_hi:[1,0,1]
	v_pk_fma_f32 v[38:39], v[38:39], v[56:57], v[130:131] op_sel_hi:[1,0,1]
	v_pk_mul_f32 v[40:41], v[40:41], v[52:53]
	v_pk_mul_f32 v[38:39], v[46:47], v[38:39]
	v_pk_mul_f32 v[36:37], v[44:45], v[36:37]
	v_pk_mul_f32 v[42:43], v[42:43], v[54:55]
	v_pk_mul_f32 v[44:45], v[36:37], v[48:49]
	v_pk_mul_f32 v[46:47], v[38:39], v[50:51]
	v_cvt_pk_bf16_f32 v36, v40, v41
	v_cvt_pk_bf16_f32 v37, v42, v43
	v_cvt_pk_bf16_f32 v38, v44, v45
	v_add_u32_e32 v41, 0x90, v166
	v_cvt_pk_bf16_f32 v39, v46, v47
	ds_read_b32 v40, v163 offset:384
	v_mad_i64_i32 v[42:43], s[22:23], v41, s34, v[116:117]
	v_lshl_add_u64 v[42:43], v[42:43], 0, v[118:119]
	global_store_dwordx4 v[42:43], v[36:39], off
	s_waitcnt lgkmcnt(0)
	v_fmamk_f32 v40, v40, 0x3a000000, v233
	v_rsq_f32_e32 v40, v40
	v_add_u32_e32 v44, 0xa0, v166
	v_add_u32_e32 v45, 0xb0, v166
	v_pk_fma_f32 v[34:35], v[34:35], v[40:41], v[146:147] op_sel_hi:[1,0,1]
	v_pk_fma_f32 v[32:33], v[32:33], v[40:41], v[144:145] op_sel_hi:[1,0,1]
	v_pk_fma_f32 v[30:31], v[30:31], v[40:41], v[142:143] op_sel_hi:[1,0,1]
	v_pk_fma_f32 v[28:29], v[28:29], v[40:41], v[140:141] op_sel_hi:[1,0,1]
	v_pk_fma_f32 v[24:25], v[24:25], v[40:41], v[132:133] op_sel_hi:[1,0,1]
	v_pk_fma_f32 v[26:27], v[26:27], v[40:41], v[134:135] op_sel_hi:[1,0,1]
	v_pk_mul_f32 v[38:39], v[34:35], s[72:73] op_sel_hi:[1,0]
	v_pk_mul_f32 v[36:37], v[32:33], s[72:73] op_sel_hi:[1,0]
	v_exp_f32_e32 v38, v38
	v_exp_f32_e32 v39, v39
	v_pk_mul_f32 v[26:27], v[34:35], v[26:27]
	v_pk_mul_f32 v[24:25], v[32:33], v[24:25]
	v_pk_mul_f32 v[32:33], v[28:29], s[72:73] op_sel_hi:[1,0]
	v_pk_mul_f32 v[34:35], v[30:31], s[72:73] op_sel_hi:[1,0]
	v_exp_f32_e32 v36, v36
	v_exp_f32_e32 v37, v37
	v_exp_f32_e32 v32, v32
	v_exp_f32_e32 v33, v33
	v_exp_f32_e32 v34, v34
	v_exp_f32_e32 v35, v35
	v_pk_add_f32 v[38:39], v[38:39], 1.0 op_sel_hi:[1,0]
	v_pk_add_f32 v[36:37], v[36:37], 1.0 op_sel_hi:[1,0]
	v_rcp_f32_e32 v38, v38
	v_rcp_f32_e32 v39, v39
	v_pk_add_f32 v[32:33], v[32:33], 1.0 op_sel_hi:[1,0]
	v_pk_add_f32 v[34:35], v[34:35], 1.0 op_sel_hi:[1,0]
	v_rcp_f32_e32 v36, v36
	v_rcp_f32_e32 v37, v37
	v_rcp_f32_e32 v32, v32
	v_rcp_f32_e32 v33, v33
	v_rcp_f32_e32 v34, v34
	v_rcp_f32_e32 v35, v35
	v_pk_fma_f32 v[20:21], v[20:21], v[40:41], v[128:129] op_sel_hi:[1,0,1]
	v_pk_fma_f32 v[22:23], v[22:23], v[40:41], v[130:131] op_sel_hi:[1,0,1]
	v_pk_mul_f32 v[26:27], v[26:27], v[38:39]
	v_pk_mul_f32 v[22:23], v[30:31], v[22:23]
	v_pk_mul_f32 v[20:21], v[28:29], v[20:21]
	v_pk_mul_f32 v[24:25], v[24:25], v[36:37]
	v_pk_mul_f32 v[28:29], v[20:21], v[32:33]
	v_pk_mul_f32 v[30:31], v[22:23], v[34:35]
	v_cvt_pk_bf16_f32 v20, v24, v25
	v_cvt_pk_bf16_f32 v21, v26, v27
	v_cvt_pk_bf16_f32 v22, v28, v29
	v_mad_i64_i32 v[24:25], s[22:23], v44, s34, v[116:117]
	v_cvt_pk_bf16_f32 v23, v30, v31
	ds_read_b32 v26, v163 offset:448
	v_lshl_add_u64 v[24:25], v[24:25], 0, v[118:119]
	global_store_dwordx4 v[24:25], v[20:23], off
	s_waitcnt lgkmcnt(0)
	s_nop 0
	v_fmamk_f32 v20, v26, 0x3a000000, v233
	v_rsq_f32_e32 v20, v20
	v_mad_i64_i32 v[22:23], s[22:23], v45, s34, v[116:117]
	v_lshl_add_u64 v[22:23], v[22:23], 0, v[118:119]
	v_pk_fma_f32 v[18:19], v[18:19], v[20:21], v[146:147] op_sel_hi:[1,0,1]
	v_pk_fma_f32 v[16:17], v[16:17], v[20:21], v[144:145] op_sel_hi:[1,0,1]
	v_pk_fma_f32 v[14:15], v[14:15], v[20:21], v[142:143] op_sel_hi:[1,0,1]
	v_pk_fma_f32 v[12:13], v[12:13], v[20:21], v[140:141] op_sel_hi:[1,0,1]
	v_pk_fma_f32 v[8:9], v[8:9], v[20:21], v[132:133] op_sel_hi:[1,0,1]
	v_pk_fma_f32 v[10:11], v[10:11], v[20:21], v[134:135] op_sel_hi:[1,0,1]
	v_pk_fma_f32 v[4:5], v[4:5], v[20:21], v[128:129] op_sel_hi:[1,0,1]
	v_pk_fma_f32 v[6:7], v[6:7], v[20:21], v[130:131] op_sel_hi:[1,0,1]
	v_pk_mul_f32 v[20:21], v[16:17], s[72:73] op_sel_hi:[1,0]
	v_pk_mul_f32 v[24:25], v[18:19], s[72:73] op_sel_hi:[1,0]
	v_pk_mul_f32 v[10:11], v[18:19], v[10:11]
	v_pk_mul_f32 v[8:9], v[16:17], v[8:9]
	v_pk_mul_f32 v[16:17], v[12:13], s[72:73] op_sel_hi:[1,0]
	v_pk_mul_f32 v[18:19], v[14:15], s[72:73] op_sel_hi:[1,0]
	v_exp_f32_e32 v20, v20
	v_exp_f32_e32 v21, v21
	v_exp_f32_e32 v24, v24
	v_exp_f32_e32 v25, v25
	v_exp_f32_e32 v16, v16
	v_exp_f32_e32 v17, v17
	v_exp_f32_e32 v18, v18
	v_exp_f32_e32 v19, v19
	v_pk_add_f32 v[20:21], v[20:21], 1.0 op_sel_hi:[1,0]
	v_pk_add_f32 v[24:25], v[24:25], 1.0 op_sel_hi:[1,0]
	v_pk_add_f32 v[16:17], v[16:17], 1.0 op_sel_hi:[1,0]
	v_pk_add_f32 v[18:19], v[18:19], 1.0 op_sel_hi:[1,0]
	v_rcp_f32_e32 v20, v20
	v_rcp_f32_e32 v21, v21
	v_rcp_f32_e32 v24, v24
	v_rcp_f32_e32 v25, v25
	v_rcp_f32_e32 v16, v16
	v_rcp_f32_e32 v17, v17
	v_rcp_f32_e32 v18, v18
	v_rcp_f32_e32 v19, v19
	v_pk_mul_f32 v[6:7], v[14:15], v[6:7]
	v_pk_mul_f32 v[4:5], v[12:13], v[4:5]
	v_pk_mul_f32 v[8:9], v[8:9], v[20:21]
	v_pk_mul_f32 v[10:11], v[10:11], v[24:25]
	v_pk_mul_f32 v[12:13], v[4:5], v[16:17]
	v_pk_mul_f32 v[14:15], v[6:7], v[18:19]
	v_cvt_pk_bf16_f32 v4, v8, v9
	v_cvt_pk_bf16_f32 v5, v10, v11
	v_cvt_pk_bf16_f32 v6, v12, v13
	s_nop 0
	v_cvt_pk_bf16_f32 v7, v14, v15
	global_store_dwordx4 v[22:23], v[4:7], off
	s_cbranch_vccnz .LBB0_262
	s_andn2_b64 vcc, exec, s[10:11]
	s_cbranch_vccnz .LBB0_261
	s_barrier
	s_branch .LBB0_261
